# P0 S5 table build: the 16 channels n of each state on 16 lanes (one trip of the n loop on 128 lanes instead of 16 serial trips on 8 lanes)
# speedup vs baseline: 1.0062x; 1.0050x over previous
;     __device__ __forceinline__ const float* in(int i) const { return karg_in(i); }
; __device__ __forceinline__ double dexp(double x) {
;     const double y = x * (1.0 / 256.0); double t = 1.0;
; #pragma unroll
;     for (int i = 12; i >= 1; --i) t = 1.0 + t * y * (1.0 / (double)i);
; #pragma unroll
;     for (int i = 0; i < 8; ++i) t = t * t;
;     return t;
; __device__ __forceinline__ void p0_prologue(const Ctx& C, LAS unsigned char* lds, int wave, int lane, int tid) {
;     ...
;     for (int idx = (tid < 8 ? blockIdx.x * 8 + tid : NG * NP); idx < NG * NP; idx += gridDim.x * 8) {
;         const int g = idx / NP, p = idx % NP;
;         const double lr = (double)C.in(14)[idx], li = (double)C.in(15)[idx], dt = dexp((double)C.in(16)[g]);
;         double s1, c1, s8, c8; dsincos(li * dt, s1, c1); dsincos(li * dt * 128.0, s8, c8);
;         const double er = dexp(lr * dt), lbr = er * c1, lbi = er * s1;
;         const double e8 = dexp(lr * dt * 128.0), l8r = e8 * c8, l8i = e8 * s8;
.LBB0_124:
	v_writelane_b32 v232, s3, 5
	v_lshl_add_u32 v0, s33, 9, v84
	s_mul_i32 s0, s33, 0xfffffe08
	v_writelane_b32 v232, s45, 6
	v_lshrrev_b32_e32 v2, 4, v84
	v_lshl_add_u32 v2, s33, 3, v2
	s_movk_i32 s0, 0x800
	v_writelane_b32 v232, s2, 7
	v_cmp_gt_i32_e32 vcc, 0x80, v84
	v_cmp_gt_i32_e64 s[4:5], s0, v2
	v_writelane_b32 v232, s1, 8
	s_and_b64 s[6:7], vcc, s[4:5]
	s_mov_b64 s[0:1], exec
	v_writelane_b32 v232, s0, 9
	s_and_b64 s[6:7], s[0:1], s[6:7]
	s_nop 0
	v_writelane_b32 v232, s1, 10
	s_mov_b64 exec, s[6:7]
	s_cbranch_execz .LBB0_129
	s_mov_b32 s8, 0x55555555
	s_mov_b32 s12, 0x745d1746
	s_mov_b32 s14, 0x9999999a
	s_mov_b32 s16, 0x1c71c71c
	s_mov_b32 s18, 0
	s_mov_b32 s20, 0x92492492
	s_mov_b32 s26, 0
	s_mov_b32 s2, 0x6dc9c883
	s_mov_b32 s34, 0x54442d18
	s_mov_b32 s38, 0x11111111
	s_mov_b32 s40, 0x11111111
	s_mov_b32 s48, 0x18618618
	s_mov_b32 s54, 0x16c16c17
	s_mov_b32 s56, 0x29e4129e
	s_mov_b32 s58, 0xf07c1f08
	s_mov_b32 s60, 0x1a41a41a
	s_mov_b32 s62, 0x16816817
	s_mov_b32 s64, 0x13813814
	s_mov_b32 s66, 0x1e1e1e1e
	s_mov_b32 s68, 0x1ac5701b
	s_mov_b32 s4, 0xfd017f40
	s_mov_b32 s72, 0x308158ed
	s_mov_b32 s76, 0x4046ed29
	s_mov_b32 s78, 0xb51f5e1a
	s_mov_b32 s30, 0x76b981db
	s_mov_b32 s82, 0xb4e81b4f
	s_mov_b32 s84, 0x7f9b2ce6
	s_mov_b32 s86, 0xc201756d
	s_mov_b32 s88, 0x6b015ac0
	s_mov_b32 s90, 0x25d51f87
	s_mov_b32 s92, 0x12d50a0
	s_mov_b32 s44, 0x19e0119e
	s_mov_b64 s[6:7], 0
	s_mov_b32 s9, 0x3fb55555
	s_mov_b32 s13, 0x3fb745d1
	s_mov_b32 s15, 0x3fb99999
	s_mov_b32 s17, 0x3fbc71c7
	s_mov_b32 s19, 0x3fc00000
	s_mov_b32 s21, 0x3fc24924
	s_mov_b32 s23, 0x3fc55555
	s_mov_b32 s22, s8
	s_mov_b32 s25, 0x3fc99999
	s_mov_b32 s24, s14
	s_mov_b32 s27, 0x3fd00000
	s_mov_b32 s29, 0x3fd55555
	s_mov_b32 s28, s8
	s_mov_b32 s3, 0x3fc45f30
	s_mov_b32 s35, 0xc01921fb
	s_mov_b32 s37, 0x3fa99999
	s_mov_b32 s36, s14
	s_mov_b32 s39, 0x3fa11111
	s_mov_b32 s41, 0x3f711111
	s_mov_b32 s49, 0x3f986186
	s_mov_b32 s51, 0x3f924924
	s_mov_b32 s50, s20
	s_mov_b32 s53, 0x3f8c71c7
	s_mov_b32 s52, s16
	s_mov_b32 s55, 0x3f86c16c
	s_mov_b32 s57, 0x3f829e41
	s_mov_b32 s59, 0x3f7f07c1
	s_mov_b32 s61, 0x3f7a41a4
	s_mov_b32 s63, 0x3f768168
	s_mov_b32 s65, 0x3f738138
	s_mov_b32 s67, 0x3f6e1e1e
	s_mov_b32 s69, 0x3f6ac570
	s_mov_b32 s5, 0x3f67f405
	s_mov_b32 s73, 0x3f658ed2
	s_mov_b32 s75, 0x3f638138
	s_mov_b32 s77, 0x3f61bb4a
	s_mov_b32 s79, 0x3f603091
	s_mov_b32 s31, 0x3f5dae60
	s_mov_b32 s83, 0x3f5b4e81
	s_mov_b32 s85, 0x3f5934c6
	s_mov_b32 s87, 0x3f5756ca
	s_mov_b32 s89, 0x3f55ac05
	s_mov_b32 s91, 0x3f542d66
	s_mov_b32 s93, 0xbf52d50a
	s_mov_b32 s45, 0xbf519e01
	v_mov_b32_e32 v1, 0
	s_mov_b32 s47, 0x2a00000
	s_mov_b32 s10, 0x2a20000
	s_mov_b64 s[96:97], 0x100
.LBB0_126:
	s_mov_b64 s[42:43], s[80:81]
	s_load_dwordx2 s[42:43], s[42:43], 0x70
	v_ashrrev_i32_e32 v3, 31, v2
	v_lshlrev_b64 v[8:9], 2, v[2:3]
	s_mov_b64 s[0:1], s[80:81]
	s_mov_b32 s74, s64
	s_waitcnt lgkmcnt(0)
	v_lshl_add_u64 v[4:5], s[42:43], 0, v[8:9]
	global_load_dword v11, v[4:5], off
	s_load_dwordx2 s[0:1], s[0:1], 0x78
	s_mov_b64 s[42:43], s[80:81]
	s_waitcnt lgkmcnt(0)
	v_lshl_add_u64 v[4:5], s[0:1], 0, v[8:9]
	global_load_dword v14, v[4:5], off
	s_load_dwordx2 s[0:1], s[42:43], 0x80
	v_lshrrev_b32_e32 v4, 26, v3
	v_add_u32_e32 v10, v2, v4
	v_ashrrev_i32_e32 v6, 6, v10
	v_ashrrev_i32_e32 v7, 31, v6
	s_waitcnt lgkmcnt(0)
	v_lshl_add_u64 v[4:5], v[6:7], 2, s[0:1]
	global_load_dword v16, v[4:5], off
	s_mov_b64 s[0:1], s[80:81]
	s_load_dwordx2 s[0:1], s[0:1], 0x110
	v_lshlrev_b64 v[4:5], 6, v[2:3]
	v_and_b32_e32 v3, 0xffffffc0, v10
	v_sub_u32_e32 v10, v2, v3
	v_lshlrev_b64 v[6:7], 12, v[6:7]
	s_mov_b64 s[42:43], 0
	s_waitcnt vmcnt(2)
	v_cvt_f64_f32_e32 v[12:13], v11
	v_ashrrev_i32_e32 v11, 31, v10
	s_waitcnt vmcnt(1)
	v_cvt_f64_f32_e32 v[14:15], v14
	s_waitcnt vmcnt(0)
	v_cvt_f64_f32_e32 v[16:17], v16
	v_ldexp_f64 v[16:17], v[16:17], -8
	v_fma_f64 v[18:19], v[16:17], s[8:9], 1.0
	v_mul_f64 v[18:19], v[16:17], v[18:19]
	v_fma_f64 v[18:19], v[18:19], s[12:13], 1.0
	v_mul_f64 v[18:19], v[16:17], v[18:19]
	v_fma_f64 v[18:19], v[18:19], s[14:15], 1.0
	v_mul_f64 v[18:19], v[16:17], v[18:19]
	v_fma_f64 v[18:19], v[18:19], s[16:17], 1.0
	v_mul_f64 v[18:19], v[16:17], v[18:19]
	v_fma_f64 v[18:19], v[18:19], s[18:19], 1.0
	v_mul_f64 v[18:19], v[16:17], v[18:19]
	v_fma_f64 v[18:19], v[18:19], s[20:21], 1.0
	v_mul_f64 v[18:19], v[16:17], v[18:19]
	v_fma_f64 v[18:19], v[18:19], s[22:23], 1.0
	v_mul_f64 v[18:19], v[16:17], v[18:19]
	v_fma_f64 v[18:19], v[18:19], s[24:25], 1.0
	v_mul_f64 v[18:19], v[16:17], v[18:19]
	v_fma_f64 v[18:19], v[18:19], s[26:27], 1.0
	v_mul_f64 v[18:19], v[16:17], v[18:19]
	v_fma_f64 v[18:19], v[18:19], s[28:29], 1.0
	v_mul_f64 v[18:19], v[16:17], v[18:19]
	v_fma_f64 v[18:19], v[18:19], 0.5, 1.0
	v_fma_f64 v[16:17], v[16:17], v[18:19], 1.0
	v_mul_f64 v[16:17], v[16:17], v[16:17]
	v_mul_f64 v[16:17], v[16:17], v[16:17]
	v_mul_f64 v[16:17], v[16:17], v[16:17]
	v_mul_f64 v[16:17], v[16:17], v[16:17]
	v_mul_f64 v[16:17], v[16:17], v[16:17]
	v_mul_f64 v[16:17], v[16:17], v[16:17]
	v_mul_f64 v[16:17], v[16:17], v[16:17]
	v_mul_f64 v[24:25], v[16:17], v[16:17]
	v_mul_f64 v[18:19], v[24:25], v[14:15]
	v_mul_f64 v[20:21], v[18:19], s[2:3]
	v_ldexp_f64 v[16:17], v[18:19], 7
	v_rndne_f64_e32 v[20:21], v[20:21]
	v_mul_f64 v[22:23], v[16:17], s[2:3]
	v_fma_f64 v[26:27], s[34:35], v[20:21], v[18:19]
	v_rndne_f64_e32 v[18:19], v[22:23]
	v_mul_f64 v[28:29], v[26:27], v[26:27]
	v_fmac_f64_e32 v[16:17], s[34:35], v[18:19]
	v_mul_f64 v[30:31], v[28:29], -v[26:27]
	v_mul_f64 v[22:23], v[28:29], 0.5
	v_mul_f64 v[20:21], v[16:17], v[16:17]
	v_mul_f64 v[32:33], v[30:31], s[22:23]
	v_fma_f64 v[18:19], v[28:29], -0.5, 1.0
; __device__ __forceinline__ void dsincos(double x, double& s, double& c) {
;     const double twopi = 6.283185307179586476925286766559;
;     const double k = rint(x * (1.0 / twopi)); const double r = x - k * twopi, r2 = r * r;
;     double ts = r, tc = 1.0; s = r; c = 1.0;
; #pragma unroll
;     for (int i = 1; i <= 15; ++i) { tc = -tc * r2 * (1.0 / (double)((2 * i - 1) * (2 * i))); ts = -ts * r2 * (1.0 / (double)((2 * i) * (2 * i + 1))); c += tc; s += ts; }
; }
	v_fmac_f64_e32 v[26:27], s[22:23], v[30:31]
	v_mul_f64 v[30:31], v[28:29], v[22:23]
	v_mul_f64 v[34:35], v[20:21], 0.5
	v_mul_f64 v[36:37], v[20:21], -v[16:17]
	v_mul_f64 v[32:33], v[28:29], -v[32:33]
	v_mul_f64 v[38:39], v[30:31], s[8:9]
	v_fmac_f64_e32 v[18:19], s[8:9], v[30:31]
	v_mul_f64 v[30:31], v[36:37], s[22:23]
	v_fmac_f64_e32 v[16:17], s[22:23], v[36:37]
	v_mul_f64 v[34:35], v[20:21], v[34:35]
	v_mul_f64 v[36:37], v[32:33], s[36:37]
	v_fma_f64 v[22:23], v[20:21], -0.5, 1.0
	v_fmac_f64_e32 v[26:27], s[36:37], v[32:33]
	v_mul_f64 v[32:33], v[28:29], -v[38:39]
	v_mul_f64 v[38:39], v[34:35], s[8:9]
	v_mul_f64 v[30:31], v[20:21], -v[30:31]
	v_mul_f64 v[36:37], v[28:29], -v[36:37]
	v_fmac_f64_e32 v[22:23], s[8:9], v[34:35]
	v_mul_f64 v[34:35], v[32:33], s[38:39]
	v_fmac_f64_e32 v[18:19], s[38:39], v[32:33]
	v_mul_f64 v[32:33], v[30:31], s[36:37]
	v_fmac_f64_e32 v[16:17], s[36:37], v[30:31]
	v_mul_f64 v[30:31], v[20:21], -v[38:39]
	v_mul_f64 v[38:39], v[36:37], s[48:49]
	v_mul_f64 v[34:35], v[28:29], -v[34:35]
	v_mul_f64 v[38:39], v[28:29], -v[38:39]
	v_fmac_f64_e32 v[26:27], s[48:49], v[36:37]
	v_mul_f64 v[40:41], v[34:35], s[50:51]
	v_fmac_f64_e32 v[18:19], s[50:51], v[34:35]
	v_mul_f64 v[34:35], v[38:39], s[52:53]
	v_fmac_f64_e32 v[26:27], s[52:53], v[38:39]
	v_mul_f64 v[38:39], v[28:29], -v[40:41]
	v_mul_f64 v[34:35], v[28:29], -v[34:35]
	v_mul_f64 v[40:41], v[38:39], s[54:55]
	v_fmac_f64_e32 v[18:19], s[54:55], v[38:39]
	v_mul_f64 v[38:39], v[34:35], s[56:57]
	v_fmac_f64_e32 v[26:27], s[56:57], v[34:35]
	v_mul_f64 v[34:35], v[28:29], -v[40:41]
	v_mul_f64 v[38:39], v[28:29], -v[38:39]
	v_mul_f64 v[40:41], v[34:35], s[58:59]
	v_fmac_f64_e32 v[18:19], s[58:59], v[34:35]
	v_mul_f64 v[34:35], v[38:39], s[60:61]
	v_fmac_f64_e32 v[26:27], s[60:61], v[38:39]
	v_mul_f64 v[38:39], v[28:29], -v[40:41]
	v_mul_f64 v[34:35], v[28:29], -v[34:35]
	v_mul_f64 v[40:41], v[38:39], s[62:63]
	v_fmac_f64_e32 v[18:19], s[62:63], v[38:39]
	v_mul_f64 v[38:39], v[34:35], s[64:65]
	v_fmac_f64_e32 v[26:27], s[64:65], v[34:35]
	v_mul_f64 v[34:35], v[28:29], -v[40:41]
	v_mul_f64 v[38:39], v[28:29], -v[38:39]
	v_mul_f64 v[40:41], v[34:35], s[40:41]
	v_fmac_f64_e32 v[18:19], s[40:41], v[34:35]
	v_mul_f64 v[34:35], v[38:39], s[66:67]
	v_fmac_f64_e32 v[26:27], s[66:67], v[38:39]
	v_mul_f64 v[38:39], v[28:29], -v[40:41]
	v_mul_f64 v[34:35], v[28:29], -v[34:35]
	v_mul_f64 v[40:41], v[38:39], s[68:69]
	v_fmac_f64_e32 v[18:19], s[68:69], v[38:39]
	v_mul_f64 v[38:39], v[34:35], s[4:5]
	v_fmac_f64_e32 v[26:27], s[4:5], v[34:35]
	v_mul_f64 v[34:35], v[28:29], -v[40:41]
	v_mul_f64 v[38:39], v[28:29], -v[38:39]
	v_mul_f64 v[40:41], v[34:35], s[72:73]
	v_fmac_f64_e32 v[18:19], s[72:73], v[34:35]
	v_mul_f64 v[34:35], v[38:39], s[74:75]
	v_fmac_f64_e32 v[26:27], s[74:75], v[38:39]
	v_mul_f64 v[38:39], v[28:29], -v[40:41]
	v_mul_f64 v[34:35], v[28:29], -v[34:35]
	v_mul_f64 v[40:41], v[38:39], s[76:77]
	v_fmac_f64_e32 v[18:19], s[76:77], v[38:39]
	v_mul_f64 v[38:39], v[34:35], s[78:79]
	v_fmac_f64_e32 v[26:27], s[78:79], v[34:35]
	v_mul_f64 v[34:35], v[28:29], -v[40:41]
	v_mul_f64 v[38:39], v[28:29], -v[38:39]
	v_mul_f64 v[40:41], v[34:35], s[30:31]
	v_fmac_f64_e32 v[18:19], s[30:31], v[34:35]
	v_mul_f64 v[34:35], v[38:39], s[82:83]
	v_fmac_f64_e32 v[26:27], s[82:83], v[38:39]
	v_mul_f64 v[38:39], v[28:29], -v[40:41]
	v_mul_f64 v[34:35], v[28:29], -v[34:35]
	v_mul_f64 v[40:41], v[38:39], s[84:85]
	v_fmac_f64_e32 v[18:19], s[84:85], v[38:39]
	v_mul_f64 v[38:39], v[34:35], s[86:87]
	v_fmac_f64_e32 v[26:27], s[86:87], v[34:35]
	v_mul_f64 v[34:35], v[28:29], -v[40:41]
	v_mul_f64 v[38:39], v[28:29], -v[38:39]
	v_mul_f64 v[40:41], v[34:35], s[88:89]
	v_fmac_f64_e32 v[18:19], s[88:89], v[34:35]
	v_mul_f64 v[34:35], v[38:39], s[90:91]
	v_fmac_f64_e32 v[26:27], s[90:91], v[38:39]
	v_mul_f64 v[38:39], v[28:29], v[40:41]
	v_mul_f64 v[28:29], v[28:29], v[34:35]
	v_mul_f64 v[36:37], v[30:31], s[38:39]
	v_fmac_f64_e32 v[26:27], s[44:45], v[28:29]
	v_mul_f64 v[28:29], v[20:21], -v[32:33]
	v_mul_f64 v[32:33], v[28:29], s[48:49]
	v_fmac_f64_e32 v[16:17], s[48:49], v[28:29]
	v_mul_f64 v[28:29], v[20:21], -v[36:37]
	v_fmac_f64_e32 v[22:23], s[38:39], v[30:31]
	v_mul_f64 v[30:31], v[28:29], s[50:51]
	v_fmac_f64_e32 v[22:23], s[50:51], v[28:29]
	v_mul_f64 v[28:29], v[20:21], -v[30:31]
	v_mul_f64 v[30:31], v[28:29], s[54:55]
	v_fmac_f64_e32 v[22:23], s[54:55], v[28:29]
	v_mul_f64 v[28:29], v[20:21], -v[30:31]
	v_mul_f64 v[30:31], v[28:29], s[58:59]
	v_fmac_f64_e32 v[22:23], s[58:59], v[28:29]
	v_mul_f64 v[28:29], v[20:21], -v[30:31]
	v_mul_f64 v[30:31], v[28:29], s[62:63]
	v_fmac_f64_e32 v[22:23], s[62:63], v[28:29]
	v_mul_f64 v[28:29], v[20:21], -v[30:31]
	v_mul_f64 v[30:31], v[28:29], s[40:41]
	v_fmac_f64_e32 v[22:23], s[40:41], v[28:29]
	v_mul_f64 v[28:29], v[20:21], -v[30:31]
	v_mul_f64 v[30:31], v[28:29], s[68:69]
	v_fmac_f64_e32 v[22:23], s[68:69], v[28:29]
	v_mul_f64 v[28:29], v[20:21], -v[30:31]
	v_mul_f64 v[30:31], v[28:29], s[72:73]
	v_fmac_f64_e32 v[22:23], s[72:73], v[28:29]
	v_mul_f64 v[28:29], v[20:21], -v[30:31]
	v_mul_f64 v[30:31], v[28:29], s[76:77]
	v_fmac_f64_e32 v[22:23], s[76:77], v[28:29]
	v_mul_f64 v[28:29], v[20:21], -v[30:31]
	v_mul_f64 v[30:31], v[28:29], s[30:31]
	v_fmac_f64_e32 v[22:23], s[30:31], v[28:29]
	v_mul_f64 v[28:29], v[20:21], -v[30:31]
	v_mul_f64 v[30:31], v[28:29], s[84:85]
	v_fmac_f64_e32 v[22:23], s[84:85], v[28:29]
	v_mul_f64 v[28:29], v[20:21], -v[30:31]
	v_mul_f64 v[32:33], v[20:21], -v[32:33]
	v_mul_f64 v[30:31], v[28:29], s[88:89]
	v_mul_f64 v[34:35], v[32:33], s[52:53]
	v_fmac_f64_e32 v[22:23], s[88:89], v[28:29]
	v_mul_f64 v[28:29], v[20:21], v[30:31]
; __device__ __forceinline__ double dexp(double x) {
;     const double y = x * (1.0 / 256.0); double t = 1.0;
; #pragma unroll
;     for (int i = 12; i >= 1; --i) t = 1.0 + t * y * (1.0 / (double)i);
; #pragma unroll
;     for (int i = 0; i < 8; ++i) t = t * t;
;     return t;
; }
; __device__ __forceinline__ void p0_prologue(const Ctx& C, LAS unsigned char* lds, int wave, int lane, int tid) {
;     ...
;         const double er = dexp(lr * dt), lbr = er * c1, lbi = er * s1;
;         const double e8 = dexp(lr * dt * 128.0), l8r = e8 * c8, l8i = e8 * s8;
;         C.LAM()[0 * 2048 + idx] = (float)lbr; C.LAM()[1 * 2048 + idx] = (float)lbi; C.LAM()[2 * 2048 + idx] = (float)l8r; C.LAM()[3 * 2048 + idx] = (float)l8i;
	v_mul_f64 v[24:25], v[24:25], v[12:13]
	v_fmac_f64_e32 v[16:17], s[52:53], v[32:33]
	v_mul_f64 v[32:33], v[20:21], -v[34:35]
	v_fmac_f64_e32 v[22:23], s[92:93], v[28:29]
	v_ldexp_f64 v[28:29], v[24:25], -8
	v_mul_f64 v[34:35], v[32:33], s[56:57]
	v_fma_f64 v[30:31], v[28:29], s[8:9], 1.0
	v_fmac_f64_e32 v[16:17], s[56:57], v[32:33]
	v_mul_f64 v[32:33], v[20:21], -v[34:35]
	v_mul_f64 v[30:31], v[28:29], v[30:31]
	v_mul_f64 v[34:35], v[32:33], s[60:61]
	v_fma_f64 v[30:31], v[30:31], s[12:13], 1.0
	v_fmac_f64_e32 v[16:17], s[60:61], v[32:33]
	v_mul_f64 v[32:33], v[20:21], -v[34:35]
	v_mul_f64 v[30:31], v[28:29], v[30:31]
	v_mul_f64 v[34:35], v[32:33], s[64:65]
	v_fma_f64 v[30:31], v[30:31], s[14:15], 1.0
	v_fmac_f64_e32 v[16:17], s[64:65], v[32:33]
	v_mul_f64 v[32:33], v[20:21], -v[34:35]
	v_mul_f64 v[30:31], v[28:29], v[30:31]
	v_mul_f64 v[34:35], v[32:33], s[66:67]
	v_fma_f64 v[30:31], v[30:31], s[16:17], 1.0
	v_fmac_f64_e32 v[16:17], s[66:67], v[32:33]
	v_mul_f64 v[32:33], v[20:21], -v[34:35]
	v_mul_f64 v[30:31], v[28:29], v[30:31]
	v_mul_f64 v[34:35], v[32:33], s[4:5]
	v_fma_f64 v[30:31], v[30:31], s[18:19], 1.0
	v_fmac_f64_e32 v[16:17], s[4:5], v[32:33]
	v_mul_f64 v[32:33], v[20:21], -v[34:35]
	v_mul_f64 v[30:31], v[28:29], v[30:31]
	v_mul_f64 v[34:35], v[32:33], s[74:75]
	v_fma_f64 v[30:31], v[30:31], s[20:21], 1.0
	v_fmac_f64_e32 v[16:17], s[74:75], v[32:33]
	v_mul_f64 v[32:33], v[20:21], -v[34:35]
	v_mul_f64 v[30:31], v[28:29], v[30:31]
	v_mul_f64 v[34:35], v[32:33], s[78:79]
	v_fma_f64 v[30:31], v[30:31], s[22:23], 1.0
	v_fmac_f64_e32 v[16:17], s[78:79], v[32:33]
	v_mul_f64 v[32:33], v[20:21], -v[34:35]
	v_mul_f64 v[30:31], v[28:29], v[30:31]
	v_mul_f64 v[34:35], v[32:33], s[82:83]
	v_fma_f64 v[30:31], v[30:31], s[24:25], 1.0
	v_fmac_f64_e32 v[16:17], s[82:83], v[32:33]
	v_mul_f64 v[32:33], v[20:21], -v[34:35]
	v_mul_f64 v[30:31], v[28:29], v[30:31]
	v_mul_f64 v[34:35], v[32:33], s[86:87]
	v_fma_f64 v[30:31], v[30:31], s[26:27], 1.0
	v_ldexp_f64 v[24:25], v[24:25], 7
	v_fmac_f64_e32 v[16:17], s[86:87], v[32:33]
	v_mul_f64 v[32:33], v[20:21], -v[34:35]
	v_mul_f64 v[30:31], v[28:29], v[30:31]
	v_ldexp_f64 v[24:25], v[24:25], -8
	v_mul_f64 v[34:35], v[32:33], s[90:91]
	v_fmac_f64_e32 v[16:17], s[90:91], v[32:33]
	v_fma_f64 v[30:31], v[30:31], s[28:29], 1.0
	v_fma_f64 v[32:33], v[24:25], s[8:9], 1.0
	v_mul_f64 v[30:31], v[28:29], v[30:31]
	v_mul_f64 v[32:33], v[24:25], v[32:33]
	v_fma_f64 v[30:31], v[30:31], 0.5, 1.0
	v_fma_f64 v[32:33], v[32:33], s[12:13], 1.0
	v_fma_f64 v[28:29], v[28:29], v[30:31], 1.0
	v_mul_f64 v[32:33], v[24:25], v[32:33]
	v_mul_f64 v[28:29], v[28:29], v[28:29]
	v_fma_f64 v[32:33], v[32:33], s[14:15], 1.0
	v_mul_f64 v[28:29], v[28:29], v[28:29]
	v_mul_f64 v[32:33], v[24:25], v[32:33]
	v_mul_f64 v[28:29], v[28:29], v[28:29]
	v_fma_f64 v[32:33], v[32:33], s[16:17], 1.0
	v_mul_f64 v[28:29], v[28:29], v[28:29]
	v_mul_f64 v[32:33], v[24:25], v[32:33]
	v_mul_f64 v[28:29], v[28:29], v[28:29]
	v_fma_f64 v[32:33], v[32:33], s[18:19], 1.0
	v_mul_f64 v[28:29], v[28:29], v[28:29]
	v_mul_f64 v[32:33], v[24:25], v[32:33]
	v_mul_f64 v[28:29], v[28:29], v[28:29]
	v_fma_f64 v[32:33], v[32:33], s[20:21], 1.0
	v_fmac_f64_e32 v[18:19], s[92:93], v[38:39]
	v_mul_f64 v[28:29], v[28:29], v[28:29]
	v_mul_f64 v[32:33], v[24:25], v[32:33]
	v_mul_f64 v[30:31], v[18:19], v[28:29]
	v_fma_f64 v[32:33], v[32:33], s[22:23], 1.0
	v_mul_f64 v[32:33], v[24:25], v[32:33]
	v_cvt_f32_f64_e32 v3, v[30:31]
	s_waitcnt lgkmcnt(0)
	v_lshl_add_u64 v[30:31], s[0:1], 0, v[8:9]
	s_mov_b32 s0, 0x2a40000
	v_fma_f64 v[32:33], v[32:33], s[24:25], 1.0
	v_add_co_u32_e32 v30, vcc, s0, v30
	v_mul_f64 v[32:33], v[24:25], v[32:33]
	s_nop 0
	v_addc_co_u32_e32 v31, vcc, 0, v31, vcc
	s_mov_b64 s[0:1], s[80:81]
	v_fma_f64 v[32:33], v[32:33], s[26:27], 1.0
	global_store_dword v[30:31], v3, off
	v_mul_f64 v[32:33], v[24:25], v[32:33]
	s_load_dwordx2 s[0:1], s[0:1], 0x110
	v_fma_f64 v[32:33], v[32:33], s[28:29], 1.0
	v_mul_f64 v[32:33], v[24:25], v[32:33]
	v_fma_f64 v[32:33], v[32:33], 0.5, 1.0
	v_fma_f64 v[24:25], v[24:25], v[32:33], 1.0
	v_mul_f64 v[24:25], v[24:25], v[24:25]
	s_waitcnt lgkmcnt(0)
	v_lshl_add_u64 v[30:31], s[0:1], 0, v[8:9]
	s_mov_b32 s0, 0x2a42000
	v_mul_f64 v[26:27], v[26:27], v[28:29]
	v_mul_f64 v[24:25], v[24:25], v[24:25]
	v_add_co_u32_e32 v30, vcc, s0, v30
	v_mul_f64 v[24:25], v[24:25], v[24:25]
	v_cvt_f32_f64_e32 v3, v[26:27]
	v_addc_co_u32_e32 v31, vcc, 0, v31, vcc
	s_mov_b64 s[0:1], s[80:81]
	v_mul_f64 v[24:25], v[24:25], v[24:25]
	global_store_dword v[30:31], v3, off
	v_mul_f64 v[24:25], v[24:25], v[24:25]
	s_load_dwordx2 s[0:1], s[0:1], 0x110
	v_mul_f64 v[24:25], v[24:25], v[24:25]
	v_mul_f64 v[24:25], v[24:25], v[24:25]
	v_mul_f64 v[24:25], v[24:25], v[24:25]
	v_mul_f64 v[22:23], v[22:23], v[24:25]
	v_cvt_f32_f64_e32 v3, v[22:23]
	s_waitcnt lgkmcnt(0)
	v_lshl_add_u64 v[22:23], s[0:1], 0, v[8:9]
	s_mov_b32 s0, 0x2a44000
	v_add_co_u32_e32 v22, vcc, s0, v22
	s_mov_b64 s[0:1], s[80:81]
	s_nop 0
	v_addc_co_u32_e32 v23, vcc, 0, v23, vcc
	global_store_dword v[22:23], v3, off
	v_mul_f64 v[20:21], v[20:21], v[34:35]
	s_load_dwordx2 s[0:1], s[0:1], 0x110
	v_fmac_f64_e32 v[16:17], s[44:45], v[20:21]
	v_mul_f64 v[16:17], v[16:17], v[24:25]
	v_cvt_f32_f64_e32 v3, v[16:17]
	v_fma_f64 v[16:17], v[18:19], v[28:29], -1.0
	v_mul_f64 v[18:19], v[14:15], v[14:15]
	v_mul_f64 v[20:21], v[16:17], v[12:13]
	v_fmac_f64_e32 v[18:19], v[12:13], v[12:13]
	v_fmac_f64_e32 v[20:21], v[26:27], v[14:15]
	s_waitcnt lgkmcnt(0)
; __device__ __forceinline__ bf16 f2bf(float f) { return (bf16)(cvt_pk_nv(f, 0.f) & 0xffffu); }
;     __device__ __forceinline__ const float* in(int i) const { return karg_in(i); }
; __device__ __forceinline__ void p0_prologue(const Ctx& C, LAS unsigned char* lds, int wave, int lane, int tid) {
;     ...
;         const double a = lbr - 1.0, b = lbi, den = lr * lr + li * li, cr = (a * lr + b * li) / den, ci = (b * lr - a * li) / den;
;         for (int n = 0; n < GN; ++n) {
;             const double br = (double)C.in(17)[(size_t)idx * GN + n], bi = (double)C.in(18)[(size_t)idx * GN + n];
;             C.BB()[((size_t)g * 128 + 2 * p) * GN + n] = f2bf((float)(cr * br - ci * bi));
;             C.BB()[((size_t)g * 128 + 2 * p + 1) * GN + n] = f2bf((float)(cr * bi + ci * br));
;             C.CM()[((size_t)g * GN + n) * 128 + 2 * p] = f2bf(C.in(19)[((size_t)g * GN + n) * NP + p]);
;             C.CM()[((size_t)g * GN + n) * 128 + 2 * p + 1] = f2bf(-C.in(20)[((size_t)g * GN + n) * NP + p]);
;         }
	v_lshl_add_u64 v[8:9], s[0:1], 0, v[8:9]
	v_div_scale_f64 v[22:23], s[0:1], v[18:19], v[18:19], v[20:21]
	v_rcp_f64_e32 v[24:25], v[22:23]
	s_mov_b32 s0, 0x2a46000
	v_add_co_u32_e32 v8, vcc, s0, v8
	v_mul_f64 v[14:15], v[16:17], v[14:15]
	s_nop 0
	v_addc_co_u32_e32 v9, vcc, 0, v9, vcc
	global_store_dword v[8:9], v3, off
	v_fma_f64 v[8:9], -v[22:23], v[24:25], 1.0
	v_fmac_f64_e32 v[24:25], v[24:25], v[8:9]
	v_fma_f64 v[12:13], v[26:27], v[12:13], -v[14:15]
	v_fma_f64 v[8:9], -v[22:23], v[24:25], 1.0
	v_div_scale_f64 v[14:15], s[0:1], v[18:19], v[18:19], v[12:13]
	v_fmac_f64_e32 v[24:25], v[24:25], v[8:9]
	v_div_scale_f64 v[8:9], vcc, v[20:21], v[18:19], v[20:21]
	v_rcp_f64_e32 v[16:17], v[14:15]
	v_mul_f64 v[28:29], v[8:9], v[24:25]
	v_fma_f64 v[8:9], -v[22:23], v[28:29], v[8:9]
	s_nop 0
	v_div_fmas_f64 v[8:9], v[8:9], v[24:25], v[28:29]
	v_div_fixup_f64 v[8:9], v[8:9], v[18:19], v[20:21]
	v_fma_f64 v[20:21], -v[14:15], v[16:17], 1.0
	v_fmac_f64_e32 v[16:17], v[16:17], v[20:21]
	v_fma_f64 v[20:21], -v[14:15], v[16:17], 1.0
	v_fmac_f64_e32 v[16:17], v[16:17], v[20:21]
	v_div_scale_f64 v[20:21], vcc, v[12:13], v[18:19], v[12:13]
	v_mul_f64 v[22:23], v[20:21], v[16:17]
	v_fma_f64 v[14:15], -v[14:15], v[22:23], v[20:21]
	s_nop 1
	v_div_fmas_f64 v[14:15], v[14:15], v[16:17], v[22:23]
	v_lshlrev_b32_e32 v16, 1, v10
	v_ashrrev_i32_e32 v17, 31, v16
	v_div_fixup_f64 v[12:13], v[14:15], v[18:19], v[12:13]
	v_lshlrev_b64 v[14:15], 5, v[16:17]
	v_lshlrev_b64 v[16:17], 1, v[16:17]
	v_lshlrev_b64 v[10:11], 2, v[10:11]
	v_and_b32_e32 v42, 15, v84
	v_mov_b32_e32 v43, 0
	v_lshl_add_u64 v[4:5], v[42:43], 2, v[4:5]
	v_lshl_add_u64 v[14:15], v[42:43], 1, v[14:15]
	v_lshlrev_b32_e32 v44, 8, v42
	v_mov_b32_e32 v45, 0
	v_lshl_add_u64 v[10:11], v[44:45], 0, v[10:11]
	v_lshl_add_u64 v[16:17], v[44:45], 0, v[16:17]
.LBB0_127:
	s_mov_b64 s[0:1], s[80:81]
	s_load_dwordx2 s[0:1], s[0:1], 0x88
	s_mov_b64 s[70:71], s[80:81]
	s_mov_b64 s[94:95], s[80:81]
	s_waitcnt lgkmcnt(0)
	v_lshl_add_u64 v[18:19], s[0:1], 0, v[4:5]
	v_lshl_add_u64 v[18:19], v[18:19], 0, s[42:43]
	global_load_dword v3, v[18:19], off
	s_load_dwordx2 s[0:1], s[70:71], 0x90
	s_mov_b64 s[70:71], s[80:81]
	s_waitcnt lgkmcnt(0)
	v_lshl_add_u64 v[18:19], s[0:1], 0, v[4:5]
	v_lshl_add_u64 v[18:19], v[18:19], 0, s[42:43]
	global_load_dword v22, v[18:19], off
	s_mov_b64 s[0:1], s[80:81]
	s_load_dwordx2 s[0:1], s[0:1], 0x110
	s_add_u32 s42, s42, 4
	s_addc_u32 s43, s43, 0
	s_cmp_eq_u32 s42, 64
	s_waitcnt lgkmcnt(0)
	v_lshl_add_u64 v[18:19], s[0:1], 0, v[6:7]
	v_lshl_add_u64 v[18:19], v[18:19], 0, v[14:15]
	v_add_co_u32_e32 v18, vcc, s47, v18
	s_waitcnt vmcnt(1)
	v_cvt_f64_f32_e32 v[20:21], v3
	v_addc_co_u32_e32 v19, vcc, 0, v19, vcc
	s_waitcnt vmcnt(0)
	v_cvt_f64_f32_e32 v[22:23], v22
	v_mul_f64 v[24:25], v[12:13], v[22:23]
	v_fma_f64 v[24:25], v[8:9], v[20:21], -v[24:25]
	v_cvt_f32_f64_e32 v3, v[24:25]
	v_cvt_pk_bf16_f32 v3, v3, v1
	global_store_short v[18:19], v3, off
	s_load_dwordx2 s[0:1], s[70:71], 0x110
	v_mul_f64 v[22:23], v[8:9], v[22:23]
	v_fmac_f64_e32 v[22:23], v[12:13], v[20:21]
	v_cvt_f32_f64_e32 v20, v[22:23]
	v_cvt_pk_bf16_f32 v20, v20, v1
	s_waitcnt lgkmcnt(0)
	v_lshl_add_u64 v[18:19], s[0:1], 0, v[6:7]
	v_lshl_add_u64 v[18:19], v[18:19], 0, v[14:15]
	v_add_co_u32_e32 v18, vcc, s47, v18
	s_mov_b64 s[70:71], s[80:81]
	s_nop 0
	v_addc_co_u32_e32 v19, vcc, 0, v19, vcc
	global_store_short v[18:19], v20, off offset:32
	s_load_dwordx2 s[0:1], s[94:95], 0x98
	v_lshl_add_u64 v[14:15], v[14:15], 0, 2
	s_waitcnt lgkmcnt(0)
	v_lshl_add_u64 v[18:19], s[0:1], 0, v[6:7]
	v_lshl_add_u64 v[18:19], v[18:19], 0, v[10:11]
	s_mov_b64 s[0:1], s[80:81]
	global_load_dword v3, v[18:19], off
	s_load_dwordx2 s[0:1], s[0:1], 0x110
	s_waitcnt vmcnt(0)
	v_cvt_pk_bf16_f32 v3, v3, v1
	s_waitcnt lgkmcnt(0)
	v_lshl_add_u64 v[18:19], s[0:1], 0, v[6:7]
	v_lshl_add_u64 v[18:19], v[18:19], 0, v[16:17]
	v_add_co_u32_e32 v18, vcc, s10, v18
	s_nop 1
	v_addc_co_u32_e32 v19, vcc, 0, v19, vcc
	global_store_short v[18:19], v3, off
	s_load_dwordx2 s[0:1], s[70:71], 0xa0
	s_waitcnt lgkmcnt(0)
	v_lshl_add_u64 v[18:19], s[0:1], 0, v[6:7]
	v_lshl_add_u64 v[18:19], v[18:19], 0, v[10:11]
	global_load_dword v3, v[18:19], off
	s_mov_b64 s[0:1], s[80:81]
	s_load_dwordx2 s[0:1], s[0:1], 0x110
	v_lshl_add_u64 v[10:11], v[10:11], 0, s[96:97]
	s_waitcnt lgkmcnt(0)
	v_lshl_add_u64 v[18:19], s[0:1], 0, v[6:7]
	v_lshl_add_u64 v[18:19], v[18:19], 0, v[16:17]
	v_add_co_u32_e32 v18, vcc, s10, v18
	v_lshl_add_u64 v[16:17], v[16:17], 0, s[96:97]
	s_nop 0
	v_addc_co_u32_e32 v19, vcc, 0, v19, vcc
	s_waitcnt vmcnt(0)
	v_xor_b32_e32 v3, 0x80000000, v3
	v_cvt_pk_bf16_f32 v3, v3, v1
	global_store_short v[18:19], v3, off offset:2
	v_add_u32_e32 v2, s46, v2
	s_movk_i32 s0, 0x7ff
	v_cmp_lt_i32_e32 vcc, s0, v2
	s_or_b64 s[6:7], vcc, s[6:7]
	s_andn2_b64 exec, exec, s[6:7]
	s_cbranch_execnz .LBB0_126
